# GU epilogue H stores marked nt (streaming, written once and read next phase)
# speedup vs baseline: 1.0051x; 1.0051x over previous
; DI unsigned cvtpk(float lo, float hi) { f32x2_t v = {lo, hi}; bf16x2_t b = __builtin_convertvector(v, bf16x2_t); return __builtin_bit_cast(unsigned, b); }
; DI float fexp2(float x) { return __builtin_amdgcn_exp2f(x); }
; DI float frcp(float x) { return __builtin_amdgcn_rcpf(x); }
;     DI void operator()(const f32x4 (&acc)[2][2][4][2], const Unit& u, int wr, int wc, int fr, int fq) const {
;     ...
;             for (int m = 0; m < 4; ++m) {
;                 const int row = row0 + ai * HALF + m * 16;
;                 const float rstd = rs8[ai * 4 + m];
;                 float hv[8];
; #pragma unroll
;                 for (int n = 0; n < 2; ++n)
; #pragma unroll
;                     for (int j = 0; j < 4; j += 2) {
;                         const float g0 = acc[ai][0][m][n][j] * rstd, u0 = acc[ai][1][m][n][j] * rstd, g1 = acc[ai][0][m][n][j + 1] * rstd, u1 = acc[ai][1][m][n][j + 1] * rstd;
;                         const float d0 = 1.0f + fexp2(fminf(-g0 * LOG2E, 60.0f)), d1 = 1.0f + fexp2(fminf(-g1 * LOG2E, 60.0f));
;                         const float rp = frcp(d0 * d1);
;                         hv[4 * n + j] = g0 * (d1 * rp) * u0; hv[4 * n + j + 1] = g1 * (d0 * rp) * u1;
;                     }
;                 u32x4 w; w.x = cvtpk(hv[0], hv[1]); w.y = cvtpk(hv[2], hv[3]); w.z = cvtpk(hv[4], hv[5]); w.w = cvtpk(hv[6], hv[7]);
;                 *(u32x4*)(H + (size_t)row * FF + col) = w;
.Lgu_noR:
	v_lshl_add_u32 v156, s49, 8, v145
	v_lshl_or_b32 v148, s48, 7, v153
	v_lshlrev_b32_e32 v149, 5, v145
	v_add_u32_e32 v149, 0x20000, v149
	ds_read_b128 v[160:163], v149
	ds_read_b128 v[164:167], v149 offset:16
	ds_read_b128 v[168:171], v149 offset:1024
	ds_read_b128 v[172:175], v149 offset:1040
	v_lshlrev_b32_e32 v148, 1, v148
	v_mad_u32_u24 v150, v156, s77, v148
	v_mov_b32_e32 v140, v150
	v_add_u32_e32 v141, 0x16000, v150
	v_add_u32_e32 v142, 0x2c000, v150
	v_add_u32_e32 v144, 0x42000, v150
	v_add_u32_e32 v146, 0xb0000, v150
	v_add_u32_e32 v152, 0xc6000, v150
	v_add_u32_e32 v154, 0xdc000, v150
	v_add_u32_e32 v158, 0xf2000, v150
	s_waitcnt lgkmcnt(0)
	v_mul_f32_e32 v176, 0xbfb8aa3b, v160
	v_mul_f32_e32 v178, 0xbfb8aa3b, v161
	v_mul_f32_e32 v180, 0xbfb8aa3b, v162
	v_mul_f32_e32 v182, 0xbfb8aa3b, v163
	v_mul_f32_e32 v184, 0xbfb8aa3b, v164
	v_mul_f32_e32 v186, 0xbfb8aa3b, v165
	v_mul_f32_e32 v188, 0xbfb8aa3b, v166
	v_mul_f32_e32 v190, 0xbfb8aa3b, v167
	v_mov_b32_e32 v208, v168
	v_mov_b32_e32 v210, v169
	v_mov_b32_e32 v212, v170
	v_mov_b32_e32 v214, v171
	v_mov_b32_e32 v216, v172
	v_mov_b32_e32 v218, v173
	v_mov_b32_e32 v220, v174
	v_mov_b32_e32 v222, v175
	v_pk_mul_f32 v[192:193], v[126:127], v[176:177] op_sel_hi:[1,0]
	v_pk_mul_f32 v[194:195], v[128:129], v[176:177] op_sel_hi:[1,0]
	v_pk_mul_f32 v[196:197], v[118:119], v[176:177] op_sel_hi:[1,0]
	v_pk_mul_f32 v[198:199], v[120:121], v[176:177] op_sel_hi:[1,0]
	v_exp_f32_e32 v192, v192
	v_exp_f32_e32 v193, v193
	v_exp_f32_e32 v194, v194
	v_exp_f32_e32 v195, v195
	v_exp_f32_e32 v196, v196
	v_exp_f32_e32 v197, v197
	v_exp_f32_e32 v198, v198
	v_exp_f32_e32 v199, v199
	v_pk_mul_f32 v[126:127], v[126:127], v[122:123]
	v_pk_mul_f32 v[128:129], v[128:129], v[124:125]
	v_pk_mul_f32 v[118:119], v[118:119], v[114:115]
	v_pk_mul_f32 v[120:121], v[120:121], v[116:117]
	v_pk_fma_f32 v[192:193], v[192:193], v[208:209], v[208:209] op_sel_hi:[1,0,0]
	v_pk_fma_f32 v[194:195], v[194:195], v[208:209], v[208:209] op_sel_hi:[1,0,0]
	v_pk_fma_f32 v[196:197], v[196:197], v[208:209], v[208:209] op_sel_hi:[1,0,0]
	v_pk_fma_f32 v[198:199], v[198:199], v[208:209], v[208:209] op_sel_hi:[1,0,0]
	v_rcp_f32_e32 v192, v192
	v_rcp_f32_e32 v193, v193
	v_rcp_f32_e32 v194, v194
	v_rcp_f32_e32 v195, v195
	v_rcp_f32_e32 v196, v196
	v_rcp_f32_e32 v197, v197
	v_rcp_f32_e32 v198, v198
	v_rcp_f32_e32 v199, v199
	s_nop 0
	v_pk_mul_f32 v[126:127], v[126:127], v[192:193]
	v_pk_mul_f32 v[128:129], v[128:129], v[194:195]
	v_pk_mul_f32 v[118:119], v[118:119], v[196:197]
	v_pk_mul_f32 v[120:121], v[120:121], v[198:199]
	v_cvt_pk_bf16_f32 v122, v126, v127
	v_cvt_pk_bf16_f32 v123, v128, v129
	v_cvt_pk_bf16_f32 v124, v118, v119
	v_cvt_pk_bf16_f32 v125, v120, v121
	global_store_dwordx4 v140, v[122:125], s[74:75] nt
	v_pk_mul_f32 v[192:193], v[110:111], v[178:179] op_sel_hi:[1,0]
	v_pk_mul_f32 v[194:195], v[112:113], v[178:179] op_sel_hi:[1,0]
	v_pk_mul_f32 v[196:197], v[102:103], v[178:179] op_sel_hi:[1,0]
	v_pk_mul_f32 v[198:199], v[104:105], v[178:179] op_sel_hi:[1,0]
	v_exp_f32_e32 v192, v192
	v_exp_f32_e32 v193, v193
	v_exp_f32_e32 v194, v194
	v_exp_f32_e32 v195, v195
	v_exp_f32_e32 v196, v196
	v_exp_f32_e32 v197, v197
	v_exp_f32_e32 v198, v198
	v_exp_f32_e32 v199, v199
	v_pk_mul_f32 v[110:111], v[110:111], v[106:107]
	v_pk_mul_f32 v[112:113], v[112:113], v[108:109]
	v_pk_mul_f32 v[102:103], v[102:103], v[98:99]
	v_pk_mul_f32 v[104:105], v[104:105], v[100:101]
	v_pk_fma_f32 v[192:193], v[192:193], v[210:211], v[210:211] op_sel_hi:[1,0,0]
	v_pk_fma_f32 v[194:195], v[194:195], v[210:211], v[210:211] op_sel_hi:[1,0,0]
	v_pk_fma_f32 v[196:197], v[196:197], v[210:211], v[210:211] op_sel_hi:[1,0,0]
	v_pk_fma_f32 v[198:199], v[198:199], v[210:211], v[210:211] op_sel_hi:[1,0,0]
	v_rcp_f32_e32 v192, v192
	v_rcp_f32_e32 v193, v193
	v_rcp_f32_e32 v194, v194
	v_rcp_f32_e32 v195, v195
	v_rcp_f32_e32 v196, v196
	v_rcp_f32_e32 v197, v197
	v_rcp_f32_e32 v198, v198
	v_rcp_f32_e32 v199, v199
	s_nop 0
	v_pk_mul_f32 v[110:111], v[110:111], v[192:193]
	v_pk_mul_f32 v[112:113], v[112:113], v[194:195]
	v_pk_mul_f32 v[102:103], v[102:103], v[196:197]
	v_pk_mul_f32 v[104:105], v[104:105], v[198:199]
	v_cvt_pk_bf16_f32 v106, v110, v111
	v_cvt_pk_bf16_f32 v107, v112, v113
	v_cvt_pk_bf16_f32 v108, v102, v103
	v_cvt_pk_bf16_f32 v109, v104, v105
	global_store_dwordx4 v141, v[106:109], s[74:75] nt
	v_pk_mul_f32 v[192:193], v[94:95], v[180:181] op_sel_hi:[1,0]
	v_pk_mul_f32 v[194:195], v[96:97], v[180:181] op_sel_hi:[1,0]
	v_pk_mul_f32 v[196:197], v[86:87], v[180:181] op_sel_hi:[1,0]
	v_pk_mul_f32 v[198:199], v[88:89], v[180:181] op_sel_hi:[1,0]
	v_exp_f32_e32 v192, v192
	v_exp_f32_e32 v193, v193
	v_exp_f32_e32 v194, v194
	v_exp_f32_e32 v195, v195
	v_exp_f32_e32 v196, v196
	v_exp_f32_e32 v197, v197
	v_exp_f32_e32 v198, v198
	v_exp_f32_e32 v199, v199
	v_pk_mul_f32 v[94:95], v[94:95], v[90:91]
	v_pk_mul_f32 v[96:97], v[96:97], v[92:93]
	v_pk_mul_f32 v[86:87], v[86:87], v[82:83]
	v_pk_mul_f32 v[88:89], v[88:89], v[84:85]
	v_pk_fma_f32 v[192:193], v[192:193], v[212:213], v[212:213] op_sel_hi:[1,0,0]
	v_pk_fma_f32 v[194:195], v[194:195], v[212:213], v[212:213] op_sel_hi:[1,0,0]
	v_pk_fma_f32 v[196:197], v[196:197], v[212:213], v[212:213] op_sel_hi:[1,0,0]
	v_pk_fma_f32 v[198:199], v[198:199], v[212:213], v[212:213] op_sel_hi:[1,0,0]
	v_rcp_f32_e32 v192, v192
	v_rcp_f32_e32 v193, v193
	v_rcp_f32_e32 v194, v194
	v_rcp_f32_e32 v195, v195
	v_rcp_f32_e32 v196, v196
	v_rcp_f32_e32 v197, v197
	v_rcp_f32_e32 v198, v198
	v_rcp_f32_e32 v199, v199
	s_nop 0
	v_pk_mul_f32 v[94:95], v[94:95], v[192:193]
	v_pk_mul_f32 v[96:97], v[96:97], v[194:195]
	v_pk_mul_f32 v[86:87], v[86:87], v[196:197]
; DI unsigned cvtpk(float lo, float hi) { f32x2_t v = {lo, hi}; bf16x2_t b = __builtin_convertvector(v, bf16x2_t); return __builtin_bit_cast(unsigned, b); }
; DI float fexp2(float x) { return __builtin_amdgcn_exp2f(x); }
; DI float frcp(float x) { return __builtin_amdgcn_rcpf(x); }
;     DI void operator()(const f32x4 (&acc)[2][2][4][2], const Unit& u, int wr, int wc, int fr, int fq) const {
;     ...
;             for (int m = 0; m < 4; ++m) {
;                 const int row = row0 + ai * HALF + m * 16;
;                 const float rstd = rs8[ai * 4 + m];
;                 float hv[8];
; #pragma unroll
;                 for (int n = 0; n < 2; ++n)
; #pragma unroll
;                     for (int j = 0; j < 4; j += 2) {
;                         const float g0 = acc[ai][0][m][n][j] * rstd, u0 = acc[ai][1][m][n][j] * rstd, g1 = acc[ai][0][m][n][j + 1] * rstd, u1 = acc[ai][1][m][n][j + 1] * rstd;
;                         const float d0 = 1.0f + fexp2(fminf(-g0 * LOG2E, 60.0f)), d1 = 1.0f + fexp2(fminf(-g1 * LOG2E, 60.0f));
;                         const float rp = frcp(d0 * d1);
;                         hv[4 * n + j] = g0 * (d1 * rp) * u0; hv[4 * n + j + 1] = g1 * (d0 * rp) * u1;
;                     }
;                 u32x4 w; w.x = cvtpk(hv[0], hv[1]); w.y = cvtpk(hv[2], hv[3]); w.z = cvtpk(hv[4], hv[5]); w.w = cvtpk(hv[6], hv[7]);
;                 *(u32x4*)(H + (size_t)row * FF + col) = w;
	v_pk_mul_f32 v[88:89], v[88:89], v[198:199]
	v_cvt_pk_bf16_f32 v90, v94, v95
	v_cvt_pk_bf16_f32 v91, v96, v97
	v_cvt_pk_bf16_f32 v92, v86, v87
	v_cvt_pk_bf16_f32 v93, v88, v89
	global_store_dwordx4 v142, v[90:93], s[74:75] nt
	v_pk_mul_f32 v[192:193], v[78:79], v[182:183] op_sel_hi:[1,0]
	v_pk_mul_f32 v[194:195], v[80:81], v[182:183] op_sel_hi:[1,0]
	v_pk_mul_f32 v[196:197], v[70:71], v[182:183] op_sel_hi:[1,0]
	v_pk_mul_f32 v[198:199], v[72:73], v[182:183] op_sel_hi:[1,0]
	v_exp_f32_e32 v192, v192
	v_exp_f32_e32 v193, v193
	v_exp_f32_e32 v194, v194
	v_exp_f32_e32 v195, v195
	v_exp_f32_e32 v196, v196
	v_exp_f32_e32 v197, v197
	v_exp_f32_e32 v198, v198
	v_exp_f32_e32 v199, v199
	v_pk_mul_f32 v[78:79], v[78:79], v[74:75]
	v_pk_mul_f32 v[80:81], v[80:81], v[76:77]
	v_pk_mul_f32 v[70:71], v[70:71], v[66:67]
	v_pk_mul_f32 v[72:73], v[72:73], v[68:69]
	v_pk_fma_f32 v[192:193], v[192:193], v[214:215], v[214:215] op_sel_hi:[1,0,0]
	v_pk_fma_f32 v[194:195], v[194:195], v[214:215], v[214:215] op_sel_hi:[1,0,0]
	v_pk_fma_f32 v[196:197], v[196:197], v[214:215], v[214:215] op_sel_hi:[1,0,0]
	v_pk_fma_f32 v[198:199], v[198:199], v[214:215], v[214:215] op_sel_hi:[1,0,0]
	v_rcp_f32_e32 v192, v192
	v_rcp_f32_e32 v193, v193
	v_rcp_f32_e32 v194, v194
	v_rcp_f32_e32 v195, v195
	v_rcp_f32_e32 v196, v196
	v_rcp_f32_e32 v197, v197
	v_rcp_f32_e32 v198, v198
	v_rcp_f32_e32 v199, v199
	s_nop 0
	v_pk_mul_f32 v[78:79], v[78:79], v[192:193]
	v_pk_mul_f32 v[80:81], v[80:81], v[194:195]
	v_pk_mul_f32 v[70:71], v[70:71], v[196:197]
	v_pk_mul_f32 v[72:73], v[72:73], v[198:199]
	v_cvt_pk_bf16_f32 v74, v78, v79
	v_cvt_pk_bf16_f32 v75, v80, v81
	v_cvt_pk_bf16_f32 v76, v70, v71
	v_cvt_pk_bf16_f32 v77, v72, v73
	global_store_dwordx4 v144, v[74:77], s[74:75] nt
	v_pk_mul_f32 v[192:193], v[62:63], v[184:185] op_sel_hi:[1,0]
	v_pk_mul_f32 v[194:195], v[64:65], v[184:185] op_sel_hi:[1,0]
	v_pk_mul_f32 v[196:197], v[54:55], v[184:185] op_sel_hi:[1,0]
	v_pk_mul_f32 v[198:199], v[56:57], v[184:185] op_sel_hi:[1,0]
	v_exp_f32_e32 v192, v192
	v_exp_f32_e32 v193, v193
	v_exp_f32_e32 v194, v194
	v_exp_f32_e32 v195, v195
	v_exp_f32_e32 v196, v196
	v_exp_f32_e32 v197, v197
	v_exp_f32_e32 v198, v198
	v_exp_f32_e32 v199, v199
	v_pk_mul_f32 v[62:63], v[62:63], v[58:59]
	v_pk_mul_f32 v[64:65], v[64:65], v[60:61]
	v_pk_mul_f32 v[54:55], v[54:55], v[50:51]
	v_pk_mul_f32 v[56:57], v[56:57], v[52:53]
	v_pk_fma_f32 v[192:193], v[192:193], v[216:217], v[216:217] op_sel_hi:[1,0,0]
	v_pk_fma_f32 v[194:195], v[194:195], v[216:217], v[216:217] op_sel_hi:[1,0,0]
	v_pk_fma_f32 v[196:197], v[196:197], v[216:217], v[216:217] op_sel_hi:[1,0,0]
	v_pk_fma_f32 v[198:199], v[198:199], v[216:217], v[216:217] op_sel_hi:[1,0,0]
	v_rcp_f32_e32 v192, v192
	v_rcp_f32_e32 v193, v193
	v_rcp_f32_e32 v194, v194
	v_rcp_f32_e32 v195, v195
	v_rcp_f32_e32 v196, v196
	v_rcp_f32_e32 v197, v197
	v_rcp_f32_e32 v198, v198
	v_rcp_f32_e32 v199, v199
	s_nop 0
	v_pk_mul_f32 v[62:63], v[62:63], v[192:193]
	v_pk_mul_f32 v[64:65], v[64:65], v[194:195]
	v_pk_mul_f32 v[54:55], v[54:55], v[196:197]
	v_pk_mul_f32 v[56:57], v[56:57], v[198:199]
	v_cvt_pk_bf16_f32 v58, v62, v63
	v_cvt_pk_bf16_f32 v59, v64, v65
	v_cvt_pk_bf16_f32 v60, v54, v55
	v_cvt_pk_bf16_f32 v61, v56, v57
	global_store_dwordx4 v146, v[58:61], s[74:75] nt
	v_pk_mul_f32 v[192:193], v[46:47], v[186:187] op_sel_hi:[1,0]
	v_pk_mul_f32 v[194:195], v[48:49], v[186:187] op_sel_hi:[1,0]
	v_pk_mul_f32 v[196:197], v[38:39], v[186:187] op_sel_hi:[1,0]
	v_pk_mul_f32 v[198:199], v[40:41], v[186:187] op_sel_hi:[1,0]
	v_exp_f32_e32 v192, v192
	v_exp_f32_e32 v193, v193
	v_exp_f32_e32 v194, v194
	v_exp_f32_e32 v195, v195
	v_exp_f32_e32 v196, v196
	v_exp_f32_e32 v197, v197
	v_exp_f32_e32 v198, v198
	v_exp_f32_e32 v199, v199
	v_pk_mul_f32 v[46:47], v[46:47], v[42:43]
	v_pk_mul_f32 v[48:49], v[48:49], v[44:45]
	v_pk_mul_f32 v[38:39], v[38:39], v[34:35]
	v_pk_mul_f32 v[40:41], v[40:41], v[36:37]
	v_pk_fma_f32 v[192:193], v[192:193], v[218:219], v[218:219] op_sel_hi:[1,0,0]
; DI unsigned cvtpk(float lo, float hi) { f32x2_t v = {lo, hi}; bf16x2_t b = __builtin_convertvector(v, bf16x2_t); return __builtin_bit_cast(unsigned, b); }
; DI float fexp2(float x) { return __builtin_amdgcn_exp2f(x); }
; DI float frcp(float x) { return __builtin_amdgcn_rcpf(x); }
;     DI void operator()(const f32x4 (&acc)[2][2][4][2], const Unit& u, int wr, int wc, int fr, int fq) const {
;     ...
;             for (int m = 0; m < 4; ++m) {
;                 const int row = row0 + ai * HALF + m * 16;
;                 const float rstd = rs8[ai * 4 + m];
;                 float hv[8];
; #pragma unroll
;                 for (int n = 0; n < 2; ++n)
; #pragma unroll
;                     for (int j = 0; j < 4; j += 2) {
;                         const float g0 = acc[ai][0][m][n][j] * rstd, u0 = acc[ai][1][m][n][j] * rstd, g1 = acc[ai][0][m][n][j + 1] * rstd, u1 = acc[ai][1][m][n][j + 1] * rstd;
;                         const float d0 = 1.0f + fexp2(fminf(-g0 * LOG2E, 60.0f)), d1 = 1.0f + fexp2(fminf(-g1 * LOG2E, 60.0f));
;                         const float rp = frcp(d0 * d1);
;                         hv[4 * n + j] = g0 * (d1 * rp) * u0; hv[4 * n + j + 1] = g1 * (d0 * rp) * u1;
;                     }
;                 u32x4 w; w.x = cvtpk(hv[0], hv[1]); w.y = cvtpk(hv[2], hv[3]); w.z = cvtpk(hv[4], hv[5]); w.w = cvtpk(hv[6], hv[7]);
;                 *(u32x4*)(H + (size_t)row * FF + col) = w;
	v_pk_fma_f32 v[194:195], v[194:195], v[218:219], v[218:219] op_sel_hi:[1,0,0]
	v_pk_fma_f32 v[196:197], v[196:197], v[218:219], v[218:219] op_sel_hi:[1,0,0]
	v_pk_fma_f32 v[198:199], v[198:199], v[218:219], v[218:219] op_sel_hi:[1,0,0]
	v_rcp_f32_e32 v192, v192
	v_rcp_f32_e32 v193, v193
	v_rcp_f32_e32 v194, v194
	v_rcp_f32_e32 v195, v195
	v_rcp_f32_e32 v196, v196
	v_rcp_f32_e32 v197, v197
	v_rcp_f32_e32 v198, v198
	v_rcp_f32_e32 v199, v199
	s_nop 0
	v_pk_mul_f32 v[46:47], v[46:47], v[192:193]
	v_pk_mul_f32 v[48:49], v[48:49], v[194:195]
	v_pk_mul_f32 v[38:39], v[38:39], v[196:197]
	v_pk_mul_f32 v[40:41], v[40:41], v[198:199]
	v_cvt_pk_bf16_f32 v42, v46, v47
	v_cvt_pk_bf16_f32 v43, v48, v49
	v_cvt_pk_bf16_f32 v44, v38, v39
	v_cvt_pk_bf16_f32 v45, v40, v41
	global_store_dwordx4 v152, v[42:45], s[74:75] nt
	v_pk_mul_f32 v[192:193], v[30:31], v[188:189] op_sel_hi:[1,0]
	v_pk_mul_f32 v[194:195], v[32:33], v[188:189] op_sel_hi:[1,0]
	v_pk_mul_f32 v[196:197], v[22:23], v[188:189] op_sel_hi:[1,0]
	v_pk_mul_f32 v[198:199], v[24:25], v[188:189] op_sel_hi:[1,0]
	v_exp_f32_e32 v192, v192
	v_exp_f32_e32 v193, v193
	v_exp_f32_e32 v194, v194
	v_exp_f32_e32 v195, v195
	v_exp_f32_e32 v196, v196
	v_exp_f32_e32 v197, v197
	v_exp_f32_e32 v198, v198
	v_exp_f32_e32 v199, v199
	v_pk_mul_f32 v[30:31], v[30:31], v[26:27]
	v_pk_mul_f32 v[32:33], v[32:33], v[28:29]
	v_pk_mul_f32 v[22:23], v[22:23], v[18:19]
	v_pk_mul_f32 v[24:25], v[24:25], v[20:21]
	v_pk_fma_f32 v[192:193], v[192:193], v[220:221], v[220:221] op_sel_hi:[1,0,0]
	v_pk_fma_f32 v[194:195], v[194:195], v[220:221], v[220:221] op_sel_hi:[1,0,0]
	v_pk_fma_f32 v[196:197], v[196:197], v[220:221], v[220:221] op_sel_hi:[1,0,0]
	v_pk_fma_f32 v[198:199], v[198:199], v[220:221], v[220:221] op_sel_hi:[1,0,0]
	v_rcp_f32_e32 v192, v192
	v_rcp_f32_e32 v193, v193
	v_rcp_f32_e32 v194, v194
	v_rcp_f32_e32 v195, v195
	v_rcp_f32_e32 v196, v196
	v_rcp_f32_e32 v197, v197
	v_rcp_f32_e32 v198, v198
	v_rcp_f32_e32 v199, v199
	s_nop 0
	v_pk_mul_f32 v[30:31], v[30:31], v[192:193]
	v_pk_mul_f32 v[32:33], v[32:33], v[194:195]
	v_pk_mul_f32 v[22:23], v[22:23], v[196:197]
	v_pk_mul_f32 v[24:25], v[24:25], v[198:199]
	v_cvt_pk_bf16_f32 v26, v30, v31
	v_cvt_pk_bf16_f32 v27, v32, v33
	v_cvt_pk_bf16_f32 v28, v22, v23
	v_cvt_pk_bf16_f32 v29, v24, v25
	global_store_dwordx4 v154, v[26:29], s[74:75] nt
	v_pk_mul_f32 v[192:193], v[14:15], v[190:191] op_sel_hi:[1,0]
	v_pk_mul_f32 v[194:195], v[16:17], v[190:191] op_sel_hi:[1,0]
	v_pk_mul_f32 v[196:197], v[6:7], v[190:191] op_sel_hi:[1,0]
	v_pk_mul_f32 v[198:199], v[8:9], v[190:191] op_sel_hi:[1,0]
	v_exp_f32_e32 v192, v192
	v_exp_f32_e32 v193, v193
	v_exp_f32_e32 v194, v194
	v_exp_f32_e32 v195, v195
	v_exp_f32_e32 v196, v196
	v_exp_f32_e32 v197, v197
	v_exp_f32_e32 v198, v198
	v_exp_f32_e32 v199, v199
	v_pk_mul_f32 v[14:15], v[14:15], v[10:11]
	v_pk_mul_f32 v[16:17], v[16:17], v[12:13]
	v_pk_mul_f32 v[6:7], v[6:7], v[2:3]
	v_pk_mul_f32 v[8:9], v[8:9], v[4:5]
	v_pk_fma_f32 v[192:193], v[192:193], v[222:223], v[222:223] op_sel_hi:[1,0,0]
	v_pk_fma_f32 v[194:195], v[194:195], v[222:223], v[222:223] op_sel_hi:[1,0,0]
	v_pk_fma_f32 v[196:197], v[196:197], v[222:223], v[222:223] op_sel_hi:[1,0,0]
	v_pk_fma_f32 v[198:199], v[198:199], v[222:223], v[222:223] op_sel_hi:[1,0,0]
	v_rcp_f32_e32 v192, v192
	v_rcp_f32_e32 v193, v193
	v_rcp_f32_e32 v194, v194
	v_rcp_f32_e32 v195, v195
	v_rcp_f32_e32 v196, v196
	v_rcp_f32_e32 v197, v197
	v_rcp_f32_e32 v198, v198
	v_rcp_f32_e32 v199, v199
	s_nop 0
	v_pk_mul_f32 v[14:15], v[14:15], v[192:193]
	v_pk_mul_f32 v[16:17], v[16:17], v[194:195]
	v_pk_mul_f32 v[6:7], v[6:7], v[196:197]
	v_pk_mul_f32 v[8:9], v[8:9], v[198:199]
	v_cvt_pk_bf16_f32 v10, v14, v15
	v_cvt_pk_bf16_f32 v11, v16, v17
	v_cvt_pk_bf16_f32 v12, v6, v7
	v_cvt_pk_bf16_f32 v13, v8, v9
	global_store_dwordx4 v158, v[10:13], s[74:75] nt
	s_andn2_b64 vcc, exec, s[4:5]
	s_mov_b64 s[6:7], -1
	s_cbranch_vccnz .LBB0_663
	s_andn2_b64 vcc, exec, s[0:1]
	s_cbranch_vccnz .LBB0_662
	s_barrier
	s_branch .LBB0_662
